# ymix outputs of moba and phase 5 stored non-temporal so that fewer dirty L2 lines are left for the write-back of grid barrier 5
# baseline (speedup 1.0000x reference)
.Lmoba_dq_pub_skip:
	s_mov_b64 exec, s[98:99]
	global_load_dwordx4 v[0:3], v[180:181], off offset:3072
	global_load_dwordx4 v[4:7], v[180:181], off offset:3104
	v_and_or_b32 v8, v196, 64, v201
	v_lshlrev_b32_e32 v8, 2, v8
	ds_bpermute_b32 v18, v8, v80
	global_load_dwordx4 v[8:11], v[180:181], off offset:3136
	global_load_dwordx4 v[12:15], v[180:181], off offset:3168
	v_lshlrev_b64 v[16:17], 11, v[182:183]
	v_lshl_add_u64 v[16:17], s[68:69], 0, v[16:17]
	v_lshlrev_b32_e32 v32, 1, v185
	s_waitcnt lgkmcnt(0)
	v_div_scale_f32 v19, s[0:1], v18, v18, 1.0
	v_rcp_f32_e32 v20, v19
	v_div_scale_f32 v21, vcc, 1.0, v18, 1.0
	v_lshl_add_u64 v[16:17], v[16:17], 0, s[62:63]
	v_fma_f32 v22, -v19, v20, 1.0
	v_fmac_f32_e32 v20, v22, v20
	v_mul_f32_e32 v22, v21, v20
	v_fma_f32 v23, -v19, v22, v21
	v_fmac_f32_e32 v22, v23, v20
	v_fma_f32 v19, -v19, v22, v21
	v_div_fmas_f32 v19, v19, v20, v22
	v_div_fixup_f32 v18, v19, v18, 1.0
	v_lshl_add_u64 v[16:17], v[16:17], 0, v[32:33]
	v_pk_mul_f32 v[20:21], v[64:65], v[18:19] op_sel_hi:[1,0]
	v_pk_mul_f32 v[22:23], v[66:67], v[18:19] op_sel_hi:[1,0]
	v_pk_mul_f32 v[24:25], v[68:69], v[18:19] op_sel_hi:[1,0]
	v_pk_mul_f32 v[26:27], v[70:71], v[18:19] op_sel_hi:[1,0]
	v_pk_mul_f32 v[28:29], v[72:73], v[18:19] op_sel_hi:[1,0]
	v_pk_mul_f32 v[30:31], v[74:75], v[18:19] op_sel_hi:[1,0]
	v_pk_mul_f32 v[34:35], v[76:77], v[18:19] op_sel_hi:[1,0]
	v_pk_mul_f32 v[36:37], v[78:79], v[18:19] op_sel_hi:[1,0]
	s_waitcnt vmcnt(3)
	v_mov_b32_e32 v19, v2
	v_mov_b32_e32 v32, v3
	s_waitcnt vmcnt(2)
	v_mov_b32_e32 v43, v6
	v_mov_b32_e32 v45, v7
	v_permlane32_swap_b32_e32 v0, v19
	v_permlane32_swap_b32_e32 v1, v32
	v_permlane32_swap_b32_e32 v4, v43
	v_permlane32_swap_b32_e32 v5, v45
	v_lshlrev_b32_e32 v2, 16, v0
	v_and_b32_e32 v3, 0xffff0000, v0
	v_lshlrev_b32_e32 v0, 16, v1
	v_and_b32_e32 v1, 0xffff0000, v1
	v_lshlrev_b32_e32 v6, 16, v19
	v_and_b32_e32 v7, 0xffff0000, v19
	v_lshlrev_b32_e32 v38, 16, v32
	v_and_b32_e32 v39, 0xffff0000, v32
	v_lshlrev_b32_e32 v40, 16, v4
	v_and_b32_e32 v41, 0xffff0000, v4
	v_lshlrev_b32_e32 v42, 16, v43
	v_and_b32_e32 v43, 0xffff0000, v43
	v_lshlrev_b32_e32 v4, 16, v5
	v_and_b32_e32 v5, 0xffff0000, v5
	v_lshlrev_b32_e32 v44, 16, v45
	v_and_b32_e32 v45, 0xffff0000, v45
	v_pk_mul_f32 v[2:3], v[20:21], v[2:3]
	v_pk_mul_f32 v[20:21], v[22:23], v[0:1]
	v_pk_mul_f32 v[6:7], v[24:25], v[6:7]
	v_pk_mul_f32 v[22:23], v[26:27], v[38:39]
	v_pk_mul_f32 v[24:25], v[28:29], v[40:41]
	v_pk_mul_f32 v[28:29], v[34:35], v[42:43]
	v_pk_mul_f32 v[26:27], v[30:31], v[4:5]
	v_pk_mul_f32 v[30:31], v[36:37], v[44:45]
	v_cvt_pk_bf16_f32 v0, v2, v3
	v_cvt_pk_bf16_f32 v1, v20, v21
	v_cvt_pk_bf16_f32 v2, v6, v7
	v_cvt_pk_bf16_f32 v3, v22, v23
	v_cvt_pk_bf16_f32 v4, v24, v25
	v_cvt_pk_bf16_f32 v6, v28, v29
	v_cvt_pk_bf16_f32 v5, v26, v27
	v_cvt_pk_bf16_f32 v7, v30, v31
	v_permlane32_swap_b32_e32 v0, v2
	v_permlane32_swap_b32_e32 v1, v3
	v_permlane32_swap_b32_e32 v4, v6
	v_permlane32_swap_b32_e32 v5, v7
	global_store_dwordx4 v[16:17], v[0:3], off nt
	global_store_dwordx4 v[16:17], v[4:7], off offset:32 nt
	s_nop 0
	v_pk_mul_f32 v[2:3], v[48:49], v[18:19] op_sel_hi:[1,0]
	s_waitcnt vmcnt(3)
	v_mov_b32_e32 v6, v10
	s_nop 1
	v_permlane32_swap_b32_e32 v8, v6
	v_mov_b32_e32 v7, v11
	s_nop 1
	v_permlane32_swap_b32_e32 v9, v7
	v_lshlrev_b32_e32 v0, 16, v8
	v_and_b32_e32 v1, 0xffff0000, v8
	v_pk_mul_f32 v[0:1], v[2:3], v[0:1]
	v_lshlrev_b32_e32 v2, 16, v9
	v_and_b32_e32 v3, 0xffff0000, v9
	v_pk_mul_f32 v[4:5], v[50:51], v[18:19] op_sel_hi:[1,0]
	v_cvt_pk_bf16_f32 v0, v0, v1
	v_pk_mul_f32 v[2:3], v[4:5], v[2:3]
	v_pk_mul_f32 v[4:5], v[52:53], v[18:19] op_sel_hi:[1,0]
	v_cvt_pk_bf16_f32 v1, v2, v3
	v_lshlrev_b32_e32 v2, 16, v6
	v_and_b32_e32 v3, 0xffff0000, v6
	s_waitcnt vmcnt(2)
	v_mov_b32_e32 v10, v14
	v_pk_mul_f32 v[2:3], v[4:5], v[2:3]
	v_lshlrev_b32_e32 v4, 16, v7
	v_and_b32_e32 v5, 0xffff0000, v7
	v_pk_mul_f32 v[6:7], v[54:55], v[18:19] op_sel_hi:[1,0]
	v_permlane32_swap_b32_e32 v12, v10
	v_mov_b32_e32 v11, v15
	v_pk_mul_f32 v[4:5], v[6:7], v[4:5]
	s_nop 0
	v_permlane32_swap_b32_e32 v13, v11
	v_cvt_pk_bf16_f32 v2, v2, v3
	v_cvt_pk_bf16_f32 v3, v4, v5
	v_lshlrev_b32_e32 v4, 16, v12
	v_and_b32_e32 v5, 0xffff0000, v12
	v_pk_mul_f32 v[6:7], v[56:57], v[18:19] op_sel_hi:[1,0]
	v_pk_mul_f32 v[8:9], v[58:59], v[18:19] op_sel_hi:[1,0]
	v_pk_mul_f32 v[4:5], v[6:7], v[4:5]
	v_lshlrev_b32_e32 v6, 16, v13
	v_and_b32_e32 v7, 0xffff0000, v13
	v_pk_mul_f32 v[6:7], v[8:9], v[6:7]
	v_cvt_pk_bf16_f32 v4, v4, v5
	v_cvt_pk_bf16_f32 v5, v6, v7
	v_lshlrev_b32_e32 v6, 16, v10
	v_and_b32_e32 v7, 0xffff0000, v10
	v_pk_mul_f32 v[8:9], v[60:61], v[18:19] op_sel_hi:[1,0]
	v_permlane32_swap_b32_e32 v0, v2
	v_pk_mul_f32 v[6:7], v[8:9], v[6:7]
	v_lshlrev_b32_e32 v8, 16, v11
	v_and_b32_e32 v9, 0xffff0000, v11
	v_pk_mul_f32 v[10:11], v[62:63], v[18:19] op_sel_hi:[1,0]
	v_cvt_pk_bf16_f32 v6, v6, v7
	v_pk_mul_f32 v[8:9], v[10:11], v[8:9]
	v_permlane32_swap_b32_e32 v1, v3
	v_cvt_pk_bf16_f32 v7, v8, v9
	v_permlane32_swap_b32_e32 v4, v6
	s_nop 0
	v_permlane32_swap_b32_e32 v5, v7
	global_store_dwordx4 v[16:17], v[0:3], off offset:64 nt
	global_store_dwordx4 v[16:17], v[4:7], off offset:96 nt

.LBB0_697:
	v_lshl_add_u64 v[2:3], s[6:7], 0, v[138:139]
	v_lshl_add_u64 v[2:3], v[2:3], 0, s[8:9]
	v_mov_b32_e32 v135, v133
	v_lshl_add_u64 v[88:89], v[2:3], 0, v[134:135]
	v_mov_b64_e32 v[2:3], s[58:59]
	v_mad_u64_u32 v[2:3], s[0:1], v136, s63, v[2:3]
	v_mov_b32_e32 v4, v3
	v_mad_u64_u32 v[4:5], s[0:1], v137, s63, v[4:5]
	v_mov_b32_e32 v3, v4
	v_lshl_add_u64 v[4:5], v[2:3], 0, s[8:9]
	v_lshl_add_u64 v[4:5], v[4:5], 0, v[134:135]
	v_add_co_u32_e32 v6, vcc, s66, v4
	v_lshl_add_u64 v[90:91], v[4:5], 0, s[16:17]
	s_nop 0
	v_addc_co_u32_e32 v7, vcc, 0, v5, vcc
	v_lshlrev_b64 v[4:5], 12, v[136:137]
	v_and_b32_e32 v1, 64, v143
	v_sub_co_u32_e32 v4, vcc, 0, v4
	global_load_dwordx4 v[8:11], v[88:89], off
	global_load_dwordx4 v[80:83], v[6:7], off offset:1024
	v_xor_b32_e32 v6, 32, v143
	v_or_b32_e32 v7, v1, v132
	v_add_u32_e32 v1, 64, v1
	v_subb_co_u32_e32 v5, vcc, 0, v5, vcc
	v_cmp_lt_i32_e32 vcc, v6, v1
	v_lshlrev_b32_e32 v7, 2, v7
	s_lshl_b32 s0, s69, 2
	v_cndmask_b32_e32 v1, v143, v6, vcc
	v_lshlrev_b32_e32 v95, 2, v1
	ds_bpermute_b32 v6, v7, v0
	ds_bpermute_b32 v7, v95, v145
	v_lshl_add_u64 v[0:1], v[2:3], 0, v[4:5]
	s_add_u32 s20, s44, s0
	s_addc_u32 s21, s45, 0
	s_add_u32 s22, s46, s0
	s_waitcnt lgkmcnt(0)
	v_add_f32_e32 v4, v145, v7
	v_fmac_f32_e32 v4, v142, v6
	v_max_f32_e64 v94, |v4|, 1.0
	v_div_scale_f32 v96, s[0:1], v94, v94, 1.0
	v_rcp_f32_e32 v97, v96
	global_load_dwordx4 v[12:15], v[88:89], off offset:32
	global_load_dwordx4 v[84:87], v[90:91], off offset:32
	v_div_scale_f32 v98, vcc, 1.0, v94, 1.0
	v_fma_f32 v99, -v96, v97, 1.0
	v_fmac_f32_e32 v97, v99, v97
	v_mul_f32_e32 v99, v98, v97
	v_fma_f32 v100, -v96, v99, v98
	v_fmac_f32_e32 v99, v100, v97
	v_fma_f32 v96, -v96, v99, v98
	v_div_fmas_f32 v96, v96, v97, v99
	v_div_fixup_f32 v124, v96, v94, 1.0
	v_pk_mul_f32 v[126:127], v[22:23], v[124:125] op_sel_hi:[1,0]
	v_pk_mul_f32 v[128:129], v[24:25], v[124:125] op_sel_hi:[1,0]
	v_pk_mul_f32 v[130:131], v[28:29], v[124:125] op_sel_hi:[1,0]
	v_pk_mul_f32 v[136:137], v[30:31], v[124:125] op_sel_hi:[1,0]
	v_lshlrev_b32_e32 v125, 2, v144
	v_pk_mul_f32 v[156:157], v[64:65], v[124:125] op_sel_hi:[1,0]
	v_pk_mul_f32 v[154:155], v[66:67], v[124:125] op_sel_hi:[1,0]
	v_add_f32_e32 v142, 0, v156
	v_add_f32_e32 v142, v157, v142
	v_add_f32_e32 v142, v154, v142
	v_pk_mul_f32 v[152:153], v[68:69], v[124:125] op_sel_hi:[1,0]
	v_add_f32_e32 v142, v155, v142
	v_add_f32_e32 v142, v152, v142
	v_pk_mul_f32 v[150:151], v[70:71], v[124:125] op_sel_hi:[1,0]
	v_add_f32_e32 v142, v153, v142
	v_add_f32_e32 v142, v150, v142
	v_pk_mul_f32 v[148:149], v[72:73], v[124:125] op_sel_hi:[1,0]
	v_add_f32_e32 v142, v151, v142
	v_add_f32_e32 v142, v148, v142
	v_pk_mul_f32 v[146:147], v[74:75], v[124:125] op_sel_hi:[1,0]
	v_add_f32_e32 v142, v149, v142
	v_add_f32_e32 v142, v146, v142
	v_pk_mul_f32 v[144:145], v[76:77], v[124:125] op_sel_hi:[1,0]
	v_add_f32_e32 v142, v147, v142
	v_add_f32_e32 v142, v144, v142
	v_pk_mul_f32 v[138:139], v[78:79], v[124:125] op_sel_hi:[1,0]
	v_add_f32_e32 v142, v145, v142
	v_add_f32_e32 v138, v138, v142
	v_add_f32_e32 v142, v139, v138
	v_pk_mul_f32 v[158:159], v[48:49], v[124:125] op_sel_hi:[1,0]
	v_pk_mul_f32 v[156:157], v[50:51], v[124:125] op_sel_hi:[1,0]
	v_add_f32_e32 v142, v158, v142
	v_add_f32_e32 v142, v159, v142
	v_add_f32_e32 v142, v156, v142
	v_pk_mul_f32 v[154:155], v[52:53], v[124:125] op_sel_hi:[1,0]
	v_add_f32_e32 v142, v157, v142
	v_add_f32_e32 v142, v154, v142
	v_pk_mul_f32 v[152:153], v[54:55], v[124:125] op_sel_hi:[1,0]
	v_add_f32_e32 v142, v155, v142
	v_add_f32_e32 v142, v152, v142
	v_pk_mul_f32 v[150:151], v[56:57], v[124:125] op_sel_hi:[1,0]
	v_add_f32_e32 v142, v153, v142
	v_add_f32_e32 v142, v150, v142
	v_pk_mul_f32 v[148:149], v[58:59], v[124:125] op_sel_hi:[1,0]
	v_add_f32_e32 v142, v151, v142
	v_add_f32_e32 v142, v148, v142
	v_pk_mul_f32 v[146:147], v[60:61], v[124:125] op_sel_hi:[1,0]
	v_add_f32_e32 v142, v149, v142
	v_add_f32_e32 v142, v146, v142
	v_pk_mul_f32 v[144:145], v[62:63], v[124:125] op_sel_hi:[1,0]
	v_add_f32_e32 v142, v147, v142
	v_add_f32_e32 v142, v144, v142
	v_add_f32_e32 v142, v145, v142
	v_pk_mul_f32 v[158:159], v[32:33], v[124:125] op_sel_hi:[1,0]
	v_pk_mul_f32 v[156:157], v[34:35], v[124:125] op_sel_hi:[1,0]
	v_add_f32_e32 v142, v158, v142
	v_add_f32_e32 v142, v159, v142
	v_add_f32_e32 v142, v156, v142
	v_pk_mul_f32 v[154:155], v[36:37], v[124:125] op_sel_hi:[1,0]
	v_add_f32_e32 v142, v157, v142
	v_add_f32_e32 v142, v154, v142
	v_pk_mul_f32 v[152:153], v[38:39], v[124:125] op_sel_hi:[1,0]
	v_add_f32_e32 v142, v155, v142
	v_add_f32_e32 v142, v152, v142
	v_pk_mul_f32 v[150:151], v[40:41], v[124:125] op_sel_hi:[1,0]
	v_add_f32_e32 v142, v153, v142
	v_add_f32_e32 v142, v150, v142
	v_pk_mul_f32 v[148:149], v[42:43], v[124:125] op_sel_hi:[1,0]
	v_add_f32_e32 v142, v151, v142
	v_add_f32_e32 v142, v148, v142
	v_pk_mul_f32 v[146:147], v[44:45], v[124:125] op_sel_hi:[1,0]
	v_add_f32_e32 v142, v149, v142
	v_add_f32_e32 v142, v146, v142
	v_pk_mul_f32 v[144:145], v[46:47], v[124:125] op_sel_hi:[1,0]
	v_add_f32_e32 v142, v147, v142
	v_add_f32_e32 v142, v144, v142
	v_add_f32_e32 v142, v145, v142
	v_pk_mul_f32 v[148:149], v[16:17], v[124:125] op_sel_hi:[1,0]
	v_pk_mul_f32 v[146:147], v[18:19], v[124:125] op_sel_hi:[1,0]
	v_add_f32_e32 v142, v148, v142
	v_add_f32_e32 v142, v149, v142
	v_add_f32_e32 v142, v146, v142
	v_pk_mul_f32 v[144:145], v[20:21], v[124:125] op_sel_hi:[1,0]
	v_add_f32_e32 v142, v147, v142
	v_add_f32_e32 v142, v144, v142
	v_add_f32_e32 v142, v145, v142
	v_add_f32_e32 v126, v126, v142
	v_add_f32_e32 v126, v127, v126
	v_add_f32_e32 v126, v128, v126
	v_pk_mul_f32 v[138:139], v[26:27], v[124:125] op_sel_hi:[1,0]
	v_add_f32_e32 v126, v129, v126
	v_add_f32_e32 v126, v138, v126
	v_add_f32_e32 v126, v139, v126
	v_add_f32_e32 v126, v130, v126
	v_add_f32_e32 v126, v131, v126
	v_add_f32_e32 v126, v136, v126
	v_add_f32_e32 v130, v137, v126
	ds_bpermute_b32 v131, v95, v130
	s_waitcnt vmcnt(1)
	v_mov_b32_e32 v132, v15
	v_mov_b32_e32 v15, v82
	v_mov_b32_e32 v82, v83
	s_waitcnt vmcnt(0)
	v_mov_b32_e32 v83, v86
	s_waitcnt lgkmcnt(0)
	v_add_f32_e32 v130, v130, v131
	v_mul_f32_e32 v130, 0x3c000000, v130
	v_mov_b32_e32 v140, v87
	v_pk_fma_f32 v[152:153], v[64:65], v[124:125], v[130:131] op_sel_hi:[1,0,0] neg_lo:[0,0,1] neg_hi:[0,0,1]
	v_permlane32_swap_b32_e32 v8, v10
	v_permlane32_swap_b32_e32 v9, v11
	v_permlane32_swap_b32_e32 v12, v14
	v_permlane32_swap_b32_e32 v13, v132
	v_permlane32_swap_b32_e32 v80, v15
	v_permlane32_swap_b32_e32 v81, v82
	v_permlane32_swap_b32_e32 v84, v83
	v_permlane32_swap_b32_e32 v85, v140
	v_pk_mul_f32 v[154:155], v[152:153], v[152:153]
	v_pk_fma_f32 v[156:157], v[66:67], v[124:125], v[130:131] op_sel_hi:[1,0,0] neg_lo:[0,0,1] neg_hi:[0,0,1]
	v_lshl_add_u64 v[92:93], v[0:1], 0, s[8:9]
	global_load_dwordx4 v[0:3], v[90:91], off offset:64
	global_load_dwordx4 v[4:7], v[90:91], off offset:96
	s_addc_u32 s23, s47, 0
	v_lshlrev_b32_e32 v118, 16, v8
	v_lshlrev_b32_e32 v116, 16, v80
	v_and_b32_e32 v119, 0xffff0000, v8
	v_and_b32_e32 v117, 0xffff0000, v80
	v_lshlrev_b32_e32 v122, 16, v9
	v_lshlrev_b32_e32 v120, 16, v81
	v_and_b32_e32 v123, 0xffff0000, v9
	v_and_b32_e32 v121, 0xffff0000, v81
	v_lshlrev_b32_e32 v110, 16, v10
	v_lshlrev_b32_e32 v108, 16, v15
	v_and_b32_e32 v111, 0xffff0000, v10
	v_and_b32_e32 v109, 0xffff0000, v15
	v_lshlrev_b32_e32 v114, 16, v11
	v_lshlrev_b32_e32 v112, 16, v82
	v_and_b32_e32 v115, 0xffff0000, v11
	v_and_b32_e32 v113, 0xffff0000, v82
	v_lshlrev_b32_e32 v102, 16, v12
	v_lshlrev_b32_e32 v100, 16, v84
	v_and_b32_e32 v103, 0xffff0000, v12
	v_and_b32_e32 v101, 0xffff0000, v84
	v_lshlrev_b32_e32 v106, 16, v13
	v_lshlrev_b32_e32 v104, 16, v85
	v_and_b32_e32 v107, 0xffff0000, v13
	v_and_b32_e32 v105, 0xffff0000, v85
	v_lshlrev_b32_e32 v98, 16, v14
	v_lshlrev_b32_e32 v96, 16, v83
	v_and_b32_e32 v99, 0xffff0000, v14
	v_and_b32_e32 v97, 0xffff0000, v83
	global_load_dwordx4 v[8:11], v125, s[20:21] offset:96
	global_load_dwordx4 v[80:83], v125, s[20:21] offset:64
	global_load_dwordx4 v[12:15], v125, s[22:23] offset:96
	global_load_dwordx4 v[84:87], v125, s[22:23] offset:64
	global_load_dwordx4 v[126:129], v125, s[20:21] offset:32
	global_load_dwordx4 v[136:139], v125, s[20:21]
	global_load_dwordx4 v[144:147], v125, s[22:23] offset:32
	global_load_dwordx4 v[148:151], v125, s[22:23]
	v_pk_mul_f32 v[158:159], v[156:157], v[156:157]
	v_pk_fma_f32 v[160:161], v[68:69], v[124:125], v[130:131] op_sel_hi:[1,0,0] neg_lo:[0,0,1] neg_hi:[0,0,1]
	v_pk_fma_f32 v[164:165], v[70:71], v[124:125], v[130:131] op_sel_hi:[1,0,0] neg_lo:[0,0,1] neg_hi:[0,0,1]
	v_pk_fma_f32 v[168:169], v[72:73], v[124:125], v[130:131] op_sel_hi:[1,0,0] neg_lo:[0,0,1] neg_hi:[0,0,1]
	v_pk_fma_f32 v[172:173], v[74:75], v[124:125], v[130:131] op_sel_hi:[1,0,0] neg_lo:[0,0,1] neg_hi:[0,0,1]
	v_pk_fma_f32 v[176:177], v[76:77], v[124:125], v[130:131] op_sel_hi:[1,0,0] neg_lo:[0,0,1] neg_hi:[0,0,1]
	v_pk_fma_f32 v[178:179], v[78:79], v[124:125], v[130:131] op_sel_hi:[1,0,0] neg_lo:[0,0,1] neg_hi:[0,0,1]
	v_pk_fma_f32 v[74:75], v[48:49], v[124:125], v[130:131] op_sel_hi:[1,0,0] neg_lo:[0,0,1] neg_hi:[0,0,1]
	v_pk_fma_f32 v[72:73], v[50:51], v[124:125], v[130:131] op_sel_hi:[1,0,0] neg_lo:[0,0,1] neg_hi:[0,0,1]
	v_pk_fma_f32 v[70:71], v[52:53], v[124:125], v[130:131] op_sel_hi:[1,0,0] neg_lo:[0,0,1] neg_hi:[0,0,1]
	v_pk_fma_f32 v[68:69], v[54:55], v[124:125], v[130:131] op_sel_hi:[1,0,0] neg_lo:[0,0,1] neg_hi:[0,0,1]
	v_pk_fma_f32 v[66:67], v[56:57], v[124:125], v[130:131] op_sel_hi:[1,0,0] neg_lo:[0,0,1] neg_hi:[0,0,1]
	v_pk_fma_f32 v[64:65], v[58:59], v[124:125], v[130:131] op_sel_hi:[1,0,0] neg_lo:[0,0,1] neg_hi:[0,0,1]
	v_pk_fma_f32 v[60:61], v[60:61], v[124:125], v[130:131] op_sel_hi:[1,0,0] neg_lo:[0,0,1] neg_hi:[0,0,1]
	v_pk_fma_f32 v[58:59], v[62:63], v[124:125], v[130:131] op_sel_hi:[1,0,0] neg_lo:[0,0,1] neg_hi:[0,0,1]
	v_pk_fma_f32 v[56:57], v[32:33], v[124:125], v[130:131] op_sel_hi:[1,0,0] neg_lo:[0,0,1] neg_hi:[0,0,1]
	v_pk_fma_f32 v[54:55], v[34:35], v[124:125], v[130:131] op_sel_hi:[1,0,0] neg_lo:[0,0,1] neg_hi:[0,0,1]
	v_pk_fma_f32 v[52:53], v[36:37], v[124:125], v[130:131] op_sel_hi:[1,0,0] neg_lo:[0,0,1] neg_hi:[0,0,1]
	v_pk_fma_f32 v[50:51], v[38:39], v[124:125], v[130:131] op_sel_hi:[1,0,0] neg_lo:[0,0,1] neg_hi:[0,0,1]
	v_pk_fma_f32 v[48:49], v[40:41], v[124:125], v[130:131] op_sel_hi:[1,0,0] neg_lo:[0,0,1] neg_hi:[0,0,1]
	v_pk_fma_f32 v[42:43], v[42:43], v[124:125], v[130:131] op_sel_hi:[1,0,0] neg_lo:[0,0,1] neg_hi:[0,0,1]
	v_pk_fma_f32 v[40:41], v[44:45], v[124:125], v[130:131] op_sel_hi:[1,0,0] neg_lo:[0,0,1] neg_hi:[0,0,1]
	v_pk_fma_f32 v[38:39], v[46:47], v[124:125], v[130:131] op_sel_hi:[1,0,0] neg_lo:[0,0,1] neg_hi:[0,0,1]
	v_pk_fma_f32 v[36:37], v[16:17], v[124:125], v[130:131] op_sel_hi:[1,0,0] neg_lo:[0,0,1] neg_hi:[0,0,1]
	v_pk_fma_f32 v[34:35], v[18:19], v[124:125], v[130:131] op_sel_hi:[1,0,0] neg_lo:[0,0,1] neg_hi:[0,0,1]
	v_pk_fma_f32 v[32:33], v[20:21], v[124:125], v[130:131] op_sel_hi:[1,0,0] neg_lo:[0,0,1] neg_hi:[0,0,1]
	v_pk_fma_f32 v[20:21], v[26:27], v[124:125], v[130:131] op_sel_hi:[1,0,0] neg_lo:[0,0,1] neg_hi:[0,0,1]
	v_pk_fma_f32 v[18:19], v[28:29], v[124:125], v[130:131] op_sel_hi:[1,0,0] neg_lo:[0,0,1] neg_hi:[0,0,1]
	v_pk_fma_f32 v[16:17], v[30:31], v[124:125], v[130:131] op_sel_hi:[1,0,0] neg_lo:[0,0,1] neg_hi:[0,0,1]
	v_pk_fma_f32 v[24:25], v[24:25], v[124:125], v[130:131] op_sel_hi:[1,0,0] neg_lo:[0,0,1] neg_hi:[0,0,1]
	v_pk_fma_f32 v[26:27], v[22:23], v[124:125], v[130:131] op_sel_hi:[1,0,0] neg_lo:[0,0,1] neg_hi:[0,0,1]
	v_add_f32_e32 v124, v154, v155
	v_add_f32_e32 v124, v158, v124
	v_pk_mul_f32 v[162:163], v[160:161], v[160:161]
	v_add_f32_e32 v124, v159, v124
	v_add_f32_e32 v124, v162, v124
	v_pk_mul_f32 v[166:167], v[164:165], v[164:165]
	v_add_f32_e32 v124, v163, v124
	v_add_f32_e32 v124, v166, v124
	v_pk_mul_f32 v[170:171], v[168:169], v[168:169]
	v_add_f32_e32 v124, v167, v124
	v_add_f32_e32 v124, v170, v124
	v_pk_mul_f32 v[174:175], v[172:173], v[172:173]
	v_add_f32_e32 v124, v171, v124
	v_add_f32_e32 v124, v174, v124
	v_pk_mul_f32 v[76:77], v[176:177], v[176:177]
	v_add_f32_e32 v124, v175, v124
	v_add_f32_e32 v76, v76, v124
	v_pk_mul_f32 v[78:79], v[178:179], v[178:179]
	v_add_f32_e32 v76, v77, v76
	v_add_f32_e32 v76, v78, v76
	v_pk_mul_f32 v[180:181], v[74:75], v[74:75]
	v_add_f32_e32 v76, v79, v76
	v_add_f32_e32 v76, v180, v76
	v_pk_mul_f32 v[182:183], v[72:73], v[72:73]
	v_add_f32_e32 v76, v181, v76
	v_add_f32_e32 v76, v182, v76
	v_pk_mul_f32 v[184:185], v[70:71], v[70:71]
	v_add_f32_e32 v76, v183, v76
	v_add_f32_e32 v76, v184, v76
	v_pk_mul_f32 v[186:187], v[68:69], v[68:69]
	v_add_f32_e32 v76, v185, v76
	v_add_f32_e32 v76, v186, v76
	v_pk_mul_f32 v[188:189], v[66:67], v[66:67]
	v_add_f32_e32 v76, v187, v76
	v_add_f32_e32 v76, v188, v76
	v_pk_mul_f32 v[190:191], v[64:65], v[64:65]
	v_add_f32_e32 v76, v189, v76
	v_add_f32_e32 v76, v190, v76
	v_pk_mul_f32 v[192:193], v[60:61], v[60:61]
	v_add_f32_e32 v76, v191, v76
	v_add_f32_e32 v76, v192, v76
	v_pk_mul_f32 v[62:63], v[58:59], v[58:59]
	v_add_f32_e32 v76, v193, v76
	v_add_f32_e32 v62, v62, v76
	v_pk_mul_f32 v[194:195], v[56:57], v[56:57]
	v_add_f32_e32 v62, v63, v62
	v_add_f32_e32 v62, v194, v62
	v_pk_mul_f32 v[196:197], v[54:55], v[54:55]
	v_add_f32_e32 v62, v195, v62
	v_add_f32_e32 v62, v196, v62
	v_pk_mul_f32 v[198:199], v[52:53], v[52:53]
	v_add_f32_e32 v62, v197, v62
	v_add_f32_e32 v62, v198, v62
	v_pk_mul_f32 v[200:201], v[50:51], v[50:51]
	v_add_f32_e32 v62, v199, v62
	v_add_f32_e32 v62, v200, v62
	v_pk_mul_f32 v[202:203], v[48:49], v[48:49]
	v_add_f32_e32 v62, v201, v62
	v_add_f32_e32 v62, v202, v62
	v_pk_mul_f32 v[204:205], v[42:43], v[42:43]
	v_add_f32_e32 v62, v203, v62
	v_add_f32_e32 v62, v204, v62
	v_pk_mul_f32 v[44:45], v[40:41], v[40:41]
	v_add_f32_e32 v62, v205, v62
	v_add_f32_e32 v44, v44, v62
	v_pk_mul_f32 v[46:47], v[38:39], v[38:39]
	v_add_f32_e32 v44, v45, v44
	v_add_f32_e32 v44, v46, v44
	v_pk_mul_f32 v[208:209], v[36:37], v[36:37]
	v_add_f32_e32 v44, v47, v44
	v_add_f32_e32 v44, v208, v44
	v_pk_mul_f32 v[210:211], v[34:35], v[34:35]
	v_add_f32_e32 v44, v209, v44
	v_add_f32_e32 v44, v210, v44
	v_pk_mul_f32 v[212:213], v[32:33], v[32:33]
	v_add_f32_e32 v44, v211, v44
	v_add_f32_e32 v44, v212, v44
	v_pk_mul_f32 v[22:23], v[26:27], v[26:27]
	v_add_f32_e32 v44, v213, v44
	v_add_f32_e32 v22, v22, v44
	v_pk_mul_f32 v[216:217], v[24:25], v[24:25]
	v_add_f32_e32 v22, v23, v22
	v_add_f32_e32 v22, v216, v22
	v_pk_mul_f32 v[214:215], v[20:21], v[20:21]
	v_add_f32_e32 v22, v217, v22
	v_add_f32_e32 v22, v214, v22
	v_pk_mul_f32 v[28:29], v[18:19], v[18:19]
	v_add_f32_e32 v22, v215, v22
	v_add_f32_e32 v22, v28, v22
	v_pk_mul_f32 v[30:31], v[16:17], v[16:17]
	v_add_f32_e32 v22, v29, v22
	v_add_f32_e32 v22, v30, v22
	v_add_f32_e32 v22, v31, v22
	ds_bpermute_b32 v23, v95, v22
	v_lshl_add_u64 v[62:63], v[92:93], 0, v[134:135]
	v_lshlrev_b32_e32 v94, 16, v132
	v_and_b32_e32 v95, 0xffff0000, v132
	global_load_dwordx4 v[44:47], v[88:89], off offset:64
	global_load_dwordx4 v[76:79], v[88:89], off offset:96
	s_waitcnt lgkmcnt(0)
	v_add_f32_e32 v22, v22, v23
	v_fmamk_f32 v22, v22, 0x3c000000, v141
	v_mul_f32_e32 v23, 0x4b800000, v22
	v_cmp_gt_f32_e32 vcc, s67, v22
	v_lshlrev_b32_e32 v30, 16, v140
	v_and_b32_e32 v31, 0xffff0000, v140
	v_cndmask_b32_e32 v22, v22, v23, vcc
	v_rsq_f32_e32 v28, v22
	v_lshl_add_u64 v[22:23], v[62:63], 0, s[18:19]
	s_add_i32 s2, s2, s28
	s_cmpk_lt_i32 s2, 0x800
	v_mul_f32_e32 v29, 0x45800000, v28
	v_cndmask_b32_e32 v28, v28, v29, vcc
	v_pk_mul_f32 v[92:93], v[152:153], v[28:29] op_sel_hi:[1,0]
	s_waitcnt vmcnt(4)
	v_pk_mul_f32 v[92:93], v[136:137], v[92:93]
	s_waitcnt vmcnt(2)
	v_pk_fma_f32 v[92:93], v[148:149], v[118:119], v[92:93]
	s_nop 0
	v_pk_mul_f32 v[92:93], v[92:93], v[116:117]
	v_pk_mul_f32 v[116:117], v[156:157], v[28:29] op_sel_hi:[1,0]
	s_nop 0
	v_pk_mul_f32 v[116:117], v[138:139], v[116:117]
	s_nop 0
	v_pk_fma_f32 v[116:117], v[150:151], v[122:123], v[116:117]
	s_nop 0
	v_pk_mul_f32 v[118:119], v[116:117], v[120:121]
	v_cvt_pk_bf16_f32 v116, v92, v93
	v_pk_mul_f32 v[92:93], v[160:161], v[28:29] op_sel_hi:[1,0]
	v_cvt_pk_bf16_f32 v117, v118, v119
	v_pk_mul_f32 v[92:93], v[126:127], v[92:93]
	s_nop 0
	v_pk_fma_f32 v[92:93], v[144:145], v[110:111], v[92:93]
	s_nop 0
	v_pk_mul_f32 v[92:93], v[92:93], v[108:109]
	v_pk_mul_f32 v[108:109], v[164:165], v[28:29] op_sel_hi:[1,0]
	v_cvt_pk_bf16_f32 v118, v92, v93
	v_pk_mul_f32 v[92:93], v[168:169], v[28:29] op_sel_hi:[1,0]
	v_pk_mul_f32 v[108:109], v[128:129], v[108:109]
	v_pk_mul_f32 v[80:81], v[80:81], v[92:93]
	v_pk_fma_f32 v[108:109], v[146:147], v[114:115], v[108:109]
	v_pk_fma_f32 v[80:81], v[84:85], v[102:103], v[80:81]
	v_pk_mul_f32 v[84:85], v[172:173], v[28:29] op_sel_hi:[1,0]
	v_pk_mul_f32 v[80:81], v[80:81], v[100:101]
	v_pk_mul_f32 v[82:83], v[82:83], v[84:85]
	v_cvt_pk_bf16_f32 v80, v80, v81
	v_pk_fma_f32 v[82:83], v[86:87], v[106:107], v[82:83]
	v_pk_mul_f32 v[108:109], v[108:109], v[112:113]
	v_pk_mul_f32 v[82:83], v[82:83], v[104:105]
	v_cvt_pk_bf16_f32 v119, v108, v109
	v_cvt_pk_bf16_f32 v81, v82, v83
	v_pk_mul_f32 v[82:83], v[176:177], v[28:29] op_sel_hi:[1,0]
	v_permlane32_swap_b32_e32 v116, v118
	v_pk_mul_f32 v[8:9], v[8:9], v[82:83]
	v_permlane32_swap_b32_e32 v117, v119
	v_pk_fma_f32 v[8:9], v[12:13], v[98:99], v[8:9]
	v_pk_mul_f32 v[12:13], v[178:179], v[28:29] op_sel_hi:[1,0]
	v_pk_mul_f32 v[8:9], v[8:9], v[96:97]
	v_pk_mul_f32 v[10:11], v[10:11], v[12:13]
	v_cvt_pk_bf16_f32 v82, v8, v9
	v_pk_fma_f32 v[10:11], v[14:15], v[94:95], v[10:11]
	v_add_co_u32_e32 v8, vcc, s68, v62
	v_pk_mul_f32 v[10:11], v[10:11], v[30:31]
	s_nop 0
	v_addc_co_u32_e32 v9, vcc, 0, v63, vcc
	v_cvt_pk_bf16_f32 v83, v10, v11
	v_permlane32_swap_b32_e32 v80, v82
	s_nop 0
	v_permlane32_swap_b32_e32 v81, v83
	global_store_dwordx4 v[8:9], v[116:119], off offset:1024 nt
	global_store_dwordx4 v[22:23], v[80:83], off offset:32 nt
	global_load_dwordx4 v[8:11], v125, s[20:21] offset:128
	s_nop 0
	global_load_dwordx4 v[12:15], v125, s[22:23] offset:128
	global_load_dwordx4 v[80:83], v125, s[20:21] offset:160
	global_load_dwordx4 v[84:87], v125, s[22:23] offset:160
	global_load_dwordx4 v[92:95], v125, s[20:21] offset:192
	global_load_dwordx4 v[96:99], v125, s[22:23] offset:192
	global_load_dwordx4 v[100:103], v125, s[20:21] offset:224
	global_load_dwordx4 v[104:107], v125, s[22:23] offset:224
	s_waitcnt vmcnt(11)
	v_mov_b32_e32 v29, v46
	s_nop 1
	v_permlane32_swap_b32_e32 v44, v29
	v_mov_b32_e32 v63, v47
	v_mov_b32_e32 v47, v2
	v_pk_mul_f32 v[74:75], v[74:75], v[28:29] op_sel_hi:[1,0]
	s_nop 0
	v_permlane32_swap_b32_e32 v0, v47
	v_mov_b32_e32 v108, v3
	v_lshlrev_b32_e32 v2, 16, v44
	v_and_b32_e32 v3, 0xffff0000, v44
	v_mov_b32_e32 v115, v6
	v_mov_b32_e32 v119, v7
	v_lshlrev_b32_e32 v6, 16, v0
	v_and_b32_e32 v7, 0xffff0000, v0
	v_permlane32_swap_b32_e32 v45, v63
	v_permlane32_swap_b32_e32 v1, v108
	v_lshlrev_b32_e32 v30, 16, v45
	v_and_b32_e32 v31, 0xffff0000, v45
	v_lshlrev_b32_e32 v0, 16, v1
	v_and_b32_e32 v1, 0xffff0000, v1
	v_lshlrev_b32_e32 v44, 16, v29
	v_and_b32_e32 v45, 0xffff0000, v29
	v_lshlrev_b32_e32 v62, 16, v63
	v_and_b32_e32 v63, 0xffff0000, v63
	s_waitcnt vmcnt(10)
	v_mov_b32_e32 v113, v78
	v_mov_b32_e32 v117, v79
	v_lshlrev_b32_e32 v46, 16, v47
	v_and_b32_e32 v47, 0xffff0000, v47
	v_lshlrev_b32_e32 v78, 16, v108
	v_and_b32_e32 v79, 0xffff0000, v108
	v_permlane32_swap_b32_e32 v76, v113
	v_permlane32_swap_b32_e32 v77, v117
	v_permlane32_swap_b32_e32 v4, v115
	v_permlane32_swap_b32_e32 v5, v119
	v_lshlrev_b32_e32 v108, 16, v76
	v_and_b32_e32 v109, 0xffff0000, v76
	v_lshlrev_b32_e32 v76, 16, v77
	v_and_b32_e32 v77, 0xffff0000, v77
	v_lshlrev_b32_e32 v110, 16, v4
	v_and_b32_e32 v111, 0xffff0000, v4
	v_lshlrev_b32_e32 v4, 16, v5
	v_and_b32_e32 v5, 0xffff0000, v5
	v_lshlrev_b32_e32 v112, 16, v113
	v_and_b32_e32 v113, 0xffff0000, v113
	v_lshlrev_b32_e32 v116, 16, v117
	v_and_b32_e32 v117, 0xffff0000, v117
	v_lshlrev_b32_e32 v114, 16, v115
	v_and_b32_e32 v115, 0xffff0000, v115
	v_lshlrev_b32_e32 v118, 16, v119
	v_and_b32_e32 v119, 0xffff0000, v119
	s_waitcnt vmcnt(7)
	v_pk_mul_f32 v[8:9], v[8:9], v[74:75]
	s_waitcnt vmcnt(6)
	v_pk_fma_f32 v[2:3], v[12:13], v[2:3], v[8:9]
	v_pk_mul_f32 v[8:9], v[64:65], v[28:29] op_sel_hi:[1,0]
	v_pk_mul_f32 v[2:3], v[2:3], v[6:7]
	v_pk_mul_f32 v[6:7], v[72:73], v[28:29] op_sel_hi:[1,0]
	s_waitcnt vmcnt(3)
	v_pk_mul_f32 v[8:9], v[94:95], v[8:9]
	v_pk_mul_f32 v[6:7], v[10:11], v[6:7]
	s_waitcnt vmcnt(2)
	v_pk_fma_f32 v[8:9], v[98:99], v[76:77], v[8:9]
	v_pk_fma_f32 v[6:7], v[14:15], v[30:31], v[6:7]
	v_pk_mul_f32 v[8:9], v[8:9], v[4:5]
	v_pk_mul_f32 v[6:7], v[6:7], v[0:1]
	v_cvt_pk_bf16_f32 v0, v2, v3
	v_cvt_pk_bf16_f32 v1, v6, v7
	v_pk_mul_f32 v[2:3], v[70:71], v[28:29] op_sel_hi:[1,0]
	v_pk_mul_f32 v[6:7], v[68:69], v[28:29] op_sel_hi:[1,0]
	v_pk_mul_f32 v[2:3], v[80:81], v[2:3]
	v_pk_mul_f32 v[6:7], v[82:83], v[6:7]
	v_pk_fma_f32 v[2:3], v[84:85], v[44:45], v[2:3]
	v_pk_fma_f32 v[6:7], v[86:87], v[62:63], v[6:7]
	v_pk_mul_f32 v[2:3], v[2:3], v[46:47]
	v_pk_mul_f32 v[6:7], v[6:7], v[78:79]
	v_cvt_pk_bf16_f32 v2, v2, v3
	v_cvt_pk_bf16_f32 v3, v6, v7
	v_pk_mul_f32 v[6:7], v[66:67], v[28:29] op_sel_hi:[1,0]
	v_cvt_pk_bf16_f32 v5, v8, v9
	v_pk_mul_f32 v[6:7], v[92:93], v[6:7]
	v_pk_mul_f32 v[8:9], v[58:59], v[28:29] op_sel_hi:[1,0]
	v_pk_fma_f32 v[6:7], v[96:97], v[108:109], v[6:7]
	s_waitcnt vmcnt(1)
	v_pk_mul_f32 v[8:9], v[102:103], v[8:9]
	v_pk_mul_f32 v[6:7], v[6:7], v[110:111]
	s_waitcnt vmcnt(0)
	v_pk_fma_f32 v[8:9], v[106:107], v[116:117], v[8:9]
	v_cvt_pk_bf16_f32 v4, v6, v7
	v_pk_mul_f32 v[6:7], v[60:61], v[28:29] op_sel_hi:[1,0]
	v_pk_mul_f32 v[8:9], v[8:9], v[118:119]
	v_pk_mul_f32 v[6:7], v[100:101], v[6:7]
	v_permlane32_swap_b32_e32 v0, v2
	v_pk_fma_f32 v[6:7], v[104:105], v[112:113], v[6:7]
	v_permlane32_swap_b32_e32 v1, v3
	v_pk_mul_f32 v[6:7], v[6:7], v[114:115]
	global_store_dwordx4 v[22:23], v[0:3], off offset:64 nt
	v_cvt_pk_bf16_f32 v6, v6, v7
	v_cvt_pk_bf16_f32 v7, v8, v9
	s_nop 0
	v_permlane32_swap_b32_e32 v4, v6
	v_permlane32_swap_b32_e32 v5, v7
	global_store_dwordx4 v[22:23], v[4:7], off offset:96 nt
	global_load_dwordx4 v[0:3], v[88:89], off offset:128
	s_nop 0
	global_load_dwordx4 v[4:7], v[90:91], off offset:128
	global_load_dwordx4 v[8:11], v[88:89], off offset:160
	global_load_dwordx4 v[12:15], v[90:91], off offset:160
	global_load_dwordx4 v[44:47], v125, s[20:21] offset:256
	global_load_dwordx4 v[58:61], v125, s[22:23] offset:256
	global_load_dwordx4 v[62:65], v125, s[20:21] offset:288
	global_load_dwordx4 v[66:69], v125, s[22:23] offset:288
	global_load_dwordx4 v[70:73], v125, s[20:21] offset:320
	global_load_dwordx4 v[74:77], v125, s[22:23] offset:320
	global_load_dwordx4 v[78:81], v125, s[20:21] offset:352
	global_load_dwordx4 v[82:85], v125, s[22:23] offset:352
	s_waitcnt vmcnt(11)
	v_mov_b32_e32 v29, v2
	s_nop 1
	v_permlane32_swap_b32_e32 v0, v29
	s_waitcnt vmcnt(10)
	v_mov_b32_e32 v31, v6
	s_waitcnt vmcnt(9)
	v_mov_b32_e32 v87, v10
	v_mov_b32_e32 v92, v11
	v_pk_mul_f32 v[10:11], v[56:57], v[28:29] op_sel_hi:[1,0]
	v_mov_b32_e32 v30, v3
	v_permlane32_swap_b32_e32 v4, v31
	v_lshlrev_b32_e32 v2, 16, v0
	s_waitcnt vmcnt(7)
	v_pk_mul_f32 v[10:11], v[44:45], v[10:11]
	v_and_b32_e32 v3, 0xffff0000, v0
	v_mov_b32_e32 v86, v7
	v_lshlrev_b32_e32 v6, 16, v4
	s_waitcnt vmcnt(6)
	v_pk_fma_f32 v[2:3], v[58:59], v[2:3], v[10:11]
	v_and_b32_e32 v7, 0xffff0000, v4
	v_permlane32_swap_b32_e32 v1, v30
	v_pk_mul_f32 v[2:3], v[2:3], v[6:7]
	v_pk_mul_f32 v[6:7], v[54:55], v[28:29] op_sel_hi:[1,0]
	v_permlane32_swap_b32_e32 v5, v86
	v_lshlrev_b32_e32 v0, 16, v1
	v_pk_mul_f32 v[6:7], v[46:47], v[6:7]
	v_and_b32_e32 v1, 0xffff0000, v1
	v_lshlrev_b32_e32 v4, 16, v5
	v_pk_fma_f32 v[0:1], v[60:61], v[0:1], v[6:7]
	v_and_b32_e32 v5, 0xffff0000, v5
	v_pk_mul_f32 v[6:7], v[52:53], v[28:29] op_sel_hi:[1,0]
	v_pk_mul_f32 v[4:5], v[0:1], v[4:5]
	v_cvt_pk_bf16_f32 v0, v2, v3
	v_lshlrev_b32_e32 v2, 16, v29
	s_waitcnt vmcnt(5)
	v_pk_mul_f32 v[6:7], v[62:63], v[6:7]
	v_and_b32_e32 v3, 0xffff0000, v29
	v_cvt_pk_bf16_f32 v1, v4, v5
	v_lshlrev_b32_e32 v4, 16, v31
	s_waitcnt vmcnt(4)
	v_pk_fma_f32 v[2:3], v[66:67], v[2:3], v[6:7]
	v_and_b32_e32 v5, 0xffff0000, v31
	v_pk_mul_f32 v[10:11], v[50:51], v[28:29] op_sel_hi:[1,0]
	v_pk_mul_f32 v[2:3], v[2:3], v[4:5]
	v_lshlrev_b32_e32 v4, 16, v30
	v_pk_mul_f32 v[10:11], v[64:65], v[10:11]
	v_and_b32_e32 v5, 0xffff0000, v30
	v_lshlrev_b32_e32 v6, 16, v86
	v_pk_fma_f32 v[4:5], v[68:69], v[4:5], v[10:11]
	v_and_b32_e32 v7, 0xffff0000, v86
	v_permlane32_swap_b32_e32 v8, v87
	v_pk_mul_f32 v[4:5], v[4:5], v[6:7]
	v_pk_mul_f32 v[10:11], v[48:49], v[28:29] op_sel_hi:[1,0]
	v_permlane32_swap_b32_e32 v12, v14
	v_cvt_pk_bf16_f32 v2, v2, v3
	v_cvt_pk_bf16_f32 v3, v4, v5
	v_lshlrev_b32_e32 v4, 16, v8
	s_waitcnt vmcnt(3)
	v_pk_mul_f32 v[10:11], v[70:71], v[10:11]
	v_and_b32_e32 v5, 0xffff0000, v8
	v_permlane32_swap_b32_e32 v9, v92
	v_lshlrev_b32_e32 v6, 16, v12
	s_waitcnt vmcnt(2)
	v_pk_fma_f32 v[4:5], v[74:75], v[4:5], v[10:11]
	v_and_b32_e32 v7, 0xffff0000, v12
	v_pk_mul_f32 v[10:11], v[42:43], v[28:29] op_sel_hi:[1,0]
	v_permlane32_swap_b32_e32 v13, v15
	v_pk_mul_f32 v[4:5], v[4:5], v[6:7]
	v_lshlrev_b32_e32 v6, 16, v9
	v_pk_mul_f32 v[10:11], v[72:73], v[10:11]
	v_and_b32_e32 v7, 0xffff0000, v9
	v_lshlrev_b32_e32 v8, 16, v13
	v_pk_fma_f32 v[6:7], v[76:77], v[6:7], v[10:11]
	v_and_b32_e32 v9, 0xffff0000, v13
	v_pk_mul_f32 v[6:7], v[6:7], v[8:9]
	v_pk_mul_f32 v[10:11], v[40:41], v[28:29] op_sel_hi:[1,0]
	v_cvt_pk_bf16_f32 v4, v4, v5
	v_cvt_pk_bf16_f32 v5, v6, v7
	v_lshlrev_b32_e32 v6, 16, v87
	s_waitcnt vmcnt(1)
	v_pk_mul_f32 v[10:11], v[78:79], v[10:11]
	v_and_b32_e32 v7, 0xffff0000, v87
	v_lshlrev_b32_e32 v8, 16, v14
	s_waitcnt vmcnt(0)
	v_pk_fma_f32 v[6:7], v[82:83], v[6:7], v[10:11]
	v_and_b32_e32 v9, 0xffff0000, v14
	v_pk_mul_f32 v[12:13], v[38:39], v[28:29] op_sel_hi:[1,0]
	v_pk_mul_f32 v[6:7], v[6:7], v[8:9]
	v_lshlrev_b32_e32 v8, 16, v92
	v_pk_mul_f32 v[12:13], v[80:81], v[12:13]
	v_and_b32_e32 v9, 0xffff0000, v92
	v_lshlrev_b32_e32 v10, 16, v15
	v_pk_fma_f32 v[8:9], v[84:85], v[8:9], v[12:13]
	v_and_b32_e32 v11, 0xffff0000, v15
	v_pk_mul_f32 v[8:9], v[8:9], v[10:11]
	v_cvt_pk_bf16_f32 v6, v6, v7
	v_cvt_pk_bf16_f32 v7, v8, v9
	v_permlane32_swap_b32_e32 v0, v2
	v_permlane32_swap_b32_e32 v1, v3
	v_permlane32_swap_b32_e32 v4, v6
	v_permlane32_swap_b32_e32 v5, v7
	global_store_dwordx4 v[22:23], v[0:3], off offset:128 nt
	global_store_dwordx4 v[22:23], v[4:7], off offset:160 nt
	global_load_dwordx4 v[0:3], v[88:89], off offset:192
	s_nop 0
	global_load_dwordx4 v[4:7], v[90:91], off offset:192
	global_load_dwordx4 v[8:11], v[88:89], off offset:224
	global_load_dwordx4 v[12:15], v[90:91], off offset:224
	global_load_dwordx4 v[38:41], v125, s[22:23] offset:384
	global_load_dwordx4 v[42:45], v125, s[20:21] offset:384
	global_load_dwordx4 v[46:49], v125, s[22:23] offset:416
	global_load_dwordx4 v[50:53], v125, s[20:21] offset:416
	global_load_dwordx4 v[54:57], v125, s[22:23] offset:448
	global_load_dwordx4 v[58:61], v125, s[20:21] offset:448
	global_load_dwordx4 v[62:65], v125, s[20:21] offset:480
	global_load_dwordx4 v[66:69], v125, s[22:23] offset:480
	s_waitcnt vmcnt(11)
	v_mov_b32_e32 v29, v2
	s_nop 1
	v_permlane32_swap_b32_e32 v0, v29
	v_mov_b32_e32 v30, v3
	s_waitcnt vmcnt(10)
	v_mov_b32_e32 v31, v6
	v_lshlrev_b32_e32 v2, 16, v0
	v_and_b32_e32 v3, 0xffff0000, v0
	v_permlane32_swap_b32_e32 v1, v30
	v_permlane32_swap_b32_e32 v4, v31
	s_waitcnt vmcnt(9)
	v_mov_b32_e32 v71, v10
	v_mov_b32_e32 v72, v11
	v_pk_mul_f32 v[10:11], v[36:37], v[28:29] op_sel_hi:[1,0]
	s_waitcnt vmcnt(7)
	v_pk_mul_f32 v[2:3], v[38:39], v[2:3]
	v_mov_b32_e32 v70, v7
	v_lshlrev_b32_e32 v6, 16, v4
	s_waitcnt vmcnt(6)
	v_pk_fma_f32 v[2:3], v[10:11], v[42:43], v[2:3]
	v_and_b32_e32 v7, 0xffff0000, v4
	v_lshlrev_b32_e32 v0, 16, v1
	v_and_b32_e32 v1, 0xffff0000, v1
	v_permlane32_swap_b32_e32 v5, v70
	v_pk_mul_f32 v[2:3], v[2:3], v[6:7]
	v_pk_mul_f32 v[6:7], v[34:35], v[28:29] op_sel_hi:[1,0]
	v_pk_mul_f32 v[0:1], v[40:41], v[0:1]
	v_lshlrev_b32_e32 v4, 16, v5
	v_pk_fma_f32 v[0:1], v[6:7], v[44:45], v[0:1]
	v_and_b32_e32 v5, 0xffff0000, v5
	v_pk_mul_f32 v[4:5], v[0:1], v[4:5]
	v_cvt_pk_bf16_f32 v0, v2, v3
	v_lshlrev_b32_e32 v2, 16, v29
	v_and_b32_e32 v3, 0xffff0000, v29
	v_pk_mul_f32 v[6:7], v[32:33], v[28:29] op_sel_hi:[1,0]
	s_waitcnt vmcnt(5)
	v_pk_mul_f32 v[2:3], v[46:47], v[2:3]
	v_cvt_pk_bf16_f32 v1, v4, v5
	v_lshlrev_b32_e32 v4, 16, v31
	s_waitcnt vmcnt(4)
	v_pk_fma_f32 v[2:3], v[6:7], v[50:51], v[2:3]
	v_and_b32_e32 v5, 0xffff0000, v31
	v_pk_mul_f32 v[2:3], v[2:3], v[4:5]
	v_lshlrev_b32_e32 v4, 16, v30
	v_and_b32_e32 v5, 0xffff0000, v30
	v_pk_mul_f32 v[10:11], v[26:27], v[28:29] op_sel_hi:[1,0]
	v_pk_mul_f32 v[4:5], v[48:49], v[4:5]
	v_lshlrev_b32_e32 v6, 16, v70
	v_pk_fma_f32 v[4:5], v[10:11], v[52:53], v[4:5]
	v_and_b32_e32 v7, 0xffff0000, v70
	v_permlane32_swap_b32_e32 v8, v71
	v_pk_mul_f32 v[4:5], v[4:5], v[6:7]
	v_cvt_pk_bf16_f32 v2, v2, v3
	v_cvt_pk_bf16_f32 v3, v4, v5
	v_lshlrev_b32_e32 v4, 16, v8
	v_and_b32_e32 v5, 0xffff0000, v8
	v_permlane32_swap_b32_e32 v12, v14
	v_pk_mul_f32 v[10:11], v[24:25], v[28:29] op_sel_hi:[1,0]
	s_waitcnt vmcnt(3)
	v_pk_mul_f32 v[4:5], v[54:55], v[4:5]
	v_permlane32_swap_b32_e32 v9, v72
	v_lshlrev_b32_e32 v6, 16, v12
	s_waitcnt vmcnt(2)
	v_pk_fma_f32 v[4:5], v[10:11], v[58:59], v[4:5]
	v_and_b32_e32 v7, 0xffff0000, v12
	v_pk_mul_f32 v[4:5], v[4:5], v[6:7]
	v_lshlrev_b32_e32 v6, 16, v9
	v_and_b32_e32 v7, 0xffff0000, v9
	v_permlane32_swap_b32_e32 v13, v15
	v_pk_mul_f32 v[10:11], v[20:21], v[28:29] op_sel_hi:[1,0]
	v_pk_mul_f32 v[6:7], v[56:57], v[6:7]
	v_lshlrev_b32_e32 v8, 16, v13
	v_and_b32_e32 v9, 0xffff0000, v13
	v_pk_fma_f32 v[6:7], v[10:11], v[60:61], v[6:7]
	v_cvt_pk_bf16_f32 v4, v4, v5
	v_pk_mul_f32 v[6:7], v[6:7], v[8:9]
	v_pk_mul_f32 v[10:11], v[18:19], v[28:29] op_sel_hi:[1,0]
	v_cvt_pk_bf16_f32 v5, v6, v7
	v_lshlrev_b32_e32 v6, 16, v71
	v_and_b32_e32 v7, 0xffff0000, v71
	s_waitcnt vmcnt(0)
	v_pk_mul_f32 v[6:7], v[66:67], v[6:7]
	v_lshlrev_b32_e32 v8, 16, v14
	v_and_b32_e32 v9, 0xffff0000, v14
	v_pk_fma_f32 v[6:7], v[10:11], v[62:63], v[6:7]
	v_pk_mul_f32 v[12:13], v[16:17], v[28:29] op_sel_hi:[1,0]
	v_pk_mul_f32 v[6:7], v[6:7], v[8:9]
	v_lshlrev_b32_e32 v8, 16, v72
	v_and_b32_e32 v9, 0xffff0000, v72
	v_pk_mul_f32 v[8:9], v[68:69], v[8:9]
	v_lshlrev_b32_e32 v10, 16, v15
	v_and_b32_e32 v11, 0xffff0000, v15
	v_pk_fma_f32 v[8:9], v[12:13], v[64:65], v[8:9]
	v_cvt_pk_bf16_f32 v6, v6, v7
	v_pk_mul_f32 v[8:9], v[8:9], v[10:11]
	v_permlane32_swap_b32_e32 v0, v2
	v_cvt_pk_bf16_f32 v7, v8, v9
	v_permlane32_swap_b32_e32 v1, v3
	v_permlane32_swap_b32_e32 v4, v6
	v_permlane32_swap_b32_e32 v5, v7
	global_store_dwordx4 v[22:23], v[0:3], off offset:192 nt
	global_store_dwordx4 v[22:23], v[4:7], off offset:224 nt
	s_cbranch_scc0 .LBB0_724
